# P6 epilogue: row-statistic cross-row reductions use v_permlane16/32_swap instead of 32 ds_bpermute round trips; on top of flat-to-global version
# baseline (speedup 1.0000x reference)
; DI u32x4 pack8(f32x4 a, f32x4 b) { u32x4 w; w.x = pk2(a[0], a[1]); w.y = pk2(a[2], a[3]); w.z = pk2(b[0], b[1]); w.w = pk2(b[2], b[3]); return w; }
;     DI void operator()(AccRef acc, const Unit& u, int wr, int wc, int fr, int fq) const {
;     ...
;         for (int it = 0; it < 8; ++it) { const int ai = it >> 2, m = it & 3, cur = it & 1;
;             if (it + 1 < 8) { int rn_ = row0 + ((it + 1) >> 2) * 128 + ((it + 1) & 3) * 16; asm volatile("" : "+v"(rn_) :: "memory"); const size_t on = (size_t)rn_ * DM + c0;
; #pragma unroll
;                 for (int bj = 0; bj < 2; ++bj)
; #pragma unroll
;                     for (int n = 0; n < 2; ++n) xb[cur ^ 1][bj][n] = *(const f32x4*)(X + on + bj * 128 + 4 * n); }
;             int row_ = row0 + ai * 128 + m * 16; asm volatile("" : "+v"(row_)); const size_t off = (size_t)row_ * DM + c0; float s1 = 0.f, s2 = 0.f;
; #pragma unroll
;             for (int bj = 0; bj < 2; ++bj) { f32x4 y[2];
; #pragma unroll
;                 for (int n = 0; n < 2; ++n) { y[n] = xb[cur][bj][n] * ALPHA + acc[ai][bj][m][n]; *(f32x4*)(Y + off + bj * 128 + 4 * n) = y[n];
;                     s1 += (y[n][0] + y[n][1]) + (y[n][2] + y[n][3]); s2 += (y[n][0] * y[n][0] + y[n][1] * y[n][1]) + (y[n][2] * y[n][2] + y[n][3] * y[n][3]); }
;                 const f32x4 g0 = *(const f32x4*)(G + c0 + bj * 128), g1 = *(const f32x4*)(G + c0 + bj * 128 + 4);
;                 *(u32x4*)(YG + off + bj * 128) = pack8(y[0] * g0, y[1] * g1); }
;             s1 += __shfl_xor(s1, 16); s1 += __shfl_xor(s1, 32); s2 += __shfl_xor(s2, 16); s2 += __shfl_xor(s2, 32);
;             if (fq == 0) { unsafeAtomicAdd(ST + (size_t)row_ * 2, s1); unsafeAtomicAdd(ST + (size_t)row_ * 2 + 1, s2); } }
.LBB0_135:
	v_lshl_add_u32 v184, s61, 8, v180
	s_mov_b64 s[14:15], s[0:1]
	v_mov_b32_e32 v134, v184
	v_lshl_or_b32 v168, s60, 8, v182
	v_ashrrev_i32_e32 v169, 31, v168
	v_ashrrev_i32_e32 v135, 31, v134
	v_lshlrev_b64 v[134:135], 12, v[134:135]
	v_lshl_add_u64 v[134:135], s[10:11], 0, v[134:135]
	v_lshlrev_b64 v[170:171], 2, v[168:169]
	v_lshl_add_u64 v[134:135], v[134:135], 0, v[170:171]
	global_load_dwordx4 v[186:189], v[134:135], off offset:16
	global_load_dwordx4 v[190:193], v[134:135], off
	global_load_dwordx4 v[150:153], v[134:135], off offset:528
	global_load_dwordx4 v[154:157], v[134:135], off offset:512
	v_or_b32_e32 v172, 16, v184
	v_mov_b32_e32 v134, v172
	s_add_u32 s58, s14, 0x17600000
	v_ashrrev_i32_e32 v135, 31, v134
	v_lshlrev_b64 v[134:135], 12, v[134:135]
	v_lshl_add_u64 v[134:135], s[10:11], 0, v[134:135]
	v_lshl_add_u64 v[138:139], v[134:135], 0, v[170:171]
	v_mov_b32_e32 v174, v184
	s_addc_u32 s59, s15, 0
	global_load_dwordx4 v[142:145], v[138:139], off offset:16
	global_load_dwordx4 v[146:149], v[138:139], off
	global_load_dwordx4 v[134:137], v[138:139], off offset:528
	s_nop 0
	global_load_dwordx4 v[138:141], v[138:139], off offset:512
	s_add_u32 s60, s14, 0xe600000
	v_ashrrev_i32_e32 v175, 31, v174
	v_lshlrev_b64 v[176:177], 10, v[174:175]
	s_addc_u32 s61, s15, 0
	v_lshl_add_u64 v[176:177], v[176:177], 0, v[168:169]
	v_lshl_add_u64 v[178:179], v[176:177], 2, s[60:61]
	v_lshl_add_u64 v[170:171], s[48:49], 0, v[170:171]
	v_lshl_add_u64 v[176:177], v[176:177], 1, s[58:59]
	s_add_u32 s56, s14, 0x3540000
	s_addc_u32 s57, s15, 0
	s_waitcnt vmcnt(0)
	v_pk_fma_f32 v[124:125], v[188:189], s[30:31], v[124:125] op_sel_hi:[1,0,1]
	v_pk_fma_f32 v[128:129], v[192:193], s[30:31], v[128:129] op_sel_hi:[1,0,1]
	v_pk_fma_f32 v[126:127], v[190:191], s[30:31], v[126:127] op_sel_hi:[1,0,1]
	v_add_f32_e32 v185, v129, v128
	v_add_f32_e32 v173, v126, v127
	v_pk_fma_f32 v[122:123], v[186:187], s[30:31], v[122:123] op_sel_hi:[1,0,1]
	v_add_f32_e32 v173, v173, v185
	v_add_f32_e32 v186, v122, v123
	v_add_f32_e32 v187, v125, v124
	v_add_f32_e32 v173, 0, v173
	v_add_f32_e32 v186, v186, v187
	v_mul_f32_e32 v185, v127, v127
	v_mul_f32_e32 v190, v128, v128
	v_add_f32_e32 v173, v173, v186
	v_mul_f32_e32 v186, v123, v123
	v_mul_f32_e32 v187, v124, v124
	v_fmac_f32_e32 v185, v126, v126
	v_fmac_f32_e32 v190, v129, v129
	v_fmac_f32_e32 v186, v122, v122
	v_fmac_f32_e32 v187, v125, v125
	global_store_dwordx4 v[178:179], v[126:129], off
	v_add_f32_e32 v185, v185, v190
	global_store_dwordx4 v[178:179], v[122:125], off offset:16
	v_add_f32_e32 v186, v186, v187
	v_add_f32_e32 v185, v185, v186
	global_load_dwordx4 v[186:189], v[170:171], off offset:16
	global_load_dwordx4 v[190:193], v[170:171], off
	v_pk_fma_f32 v[120:121], v[156:157], s[30:31], v[120:121] op_sel_hi:[1,0,1]
	v_pk_fma_f32 v[118:119], v[154:155], s[30:31], v[118:119] op_sel_hi:[1,0,1]
	v_pk_fma_f32 v[116:117], v[152:153], s[30:31], v[116:117] op_sel_hi:[1,0,1]
	v_pk_fma_f32 v[114:115], v[150:151], s[30:31], v[114:115] op_sel_hi:[1,0,1]
	s_waitcnt vmcnt(0)
	v_pk_mul_f32 v[188:189], v[124:125], v[188:189]
	v_pk_mul_f32 v[128:129], v[128:129], v[192:193]
	v_pk_mul_f32 v[126:127], v[126:127], v[190:191]
	v_pk_mul_f32 v[124:125], v[122:123], v[186:187]
	v_cvt_pk_bf16_f32 v122, v126, v127
	v_cvt_pk_bf16_f32 v123, v128, v129
	v_cvt_pk_bf16_f32 v124, v124, v125
	v_cvt_pk_bf16_f32 v125, v188, v189
	global_store_dwordx4 v[176:177], v[122:125], off
	global_store_dwordx4 v[178:179], v[118:121], off offset:512
	global_store_dwordx4 v[178:179], v[114:117], off offset:528
	v_add_f32_e32 v122, v118, v119
	v_add_f32_e32 v123, v121, v120
	v_add_f32_e32 v122, v122, v123
	v_mul_f32_e32 v123, v119, v119
	v_mul_f32_e32 v124, v120, v120
	v_fmac_f32_e32 v123, v118, v118
	v_fmac_f32_e32 v124, v121, v121
	v_add_f32_e32 v123, v123, v124
	v_add_f32_e32 v124, v114, v115
	v_add_f32_e32 v125, v117, v116
	v_add_f32_e32 v122, v173, v122
	v_add_f32_e32 v124, v124, v125
	v_add_f32_e32 v150, v122, v124
	v_mul_f32_e32 v122, v115, v115
	v_mul_f32_e32 v124, v116, v116
	v_fmac_f32_e32 v122, v114, v114
	v_fmac_f32_e32 v124, v117, v117
	v_add_f32_e32 v123, v185, v123
	v_add_f32_e32 v122, v122, v124
	v_add_f32_e32 v151, v123, v122
	global_load_dwordx4 v[122:125], v[170:171], off offset:528
	global_load_dwordx4 v[126:129], v[170:171], off offset:512
	s_waitcnt vmcnt(0)
	v_pk_mul_f32 v[124:125], v[116:117], v[124:125]
	v_pk_mul_f32 v[120:121], v[120:121], v[128:129]
	v_pk_mul_f32 v[118:119], v[118:119], v[126:127]
	v_pk_mul_f32 v[116:117], v[114:115], v[122:123]
	v_cvt_pk_bf16_f32 v114, v118, v119
	v_cvt_pk_bf16_f32 v115, v120, v121
	v_cvt_pk_bf16_f32 v116, v116, v117
	v_cvt_pk_bf16_f32 v117, v124, v125
	global_store_dwordx4 v[176:177], v[114:117], off offset:256
	s_nop 1
	v_and_b32_e32 v115, 64, v230
	v_xor_b32_e32 v114, 16, v230
	v_add_u32_e32 v115, 64, v115
	v_cmp_lt_i32_e32 vcc, v114, v115
	v_xor_b32_e32 v116, 32, v230
	s_nop 0
	v_cndmask_b32_e32 v114, v230, v114, vcc
	v_lshlrev_b32_e32 v152, 2, v114
	v_cmp_lt_i32_e32 vcc, v116, v115
	v_mov_b32_e32 v114, v150
	v_mov_b32_e32 v240, v150
	s_nop 1
	v_permlane16_swap_b32_e32 v114, v240
	s_nop 1
	v_mov_b32_dpp v114, v240 quad_perm:[0,1,2,3] row_mask:0x5 bank_mask:0xf
	s_waitcnt lgkmcnt(0)
	v_add_f32_e32 v114, v150, v114
	v_cndmask_b32_e32 v115, v230, v116, vcc
	v_mov_b32_e32 v116, v151
	v_mov_b32_e32 v240, v151
	s_nop 1
	v_permlane16_swap_b32_e32 v116, v240
	s_nop 1
	v_mov_b32_dpp v116, v240 quad_perm:[0,1,2,3] row_mask:0x5 bank_mask:0xf
	v_lshlrev_b32_e32 v153, 2, v115
	v_mov_b32_e32 v115, v114
	v_mov_b32_e32 v240, v114
	s_nop 1
	v_permlane32_swap_b32_e32 v115, v240
	s_nop 1
	v_mov_b32_dpp v115, v240 quad_perm:[0,1,2,3] row_mask:0x3 bank_mask:0xf
	s_waitcnt lgkmcnt(0)
	v_add_f32_e32 v116, v151, v116
	v_mov_b32_e32 v117, v116
	v_mov_b32_e32 v240, v116
	s_nop 1
	v_permlane32_swap_b32_e32 v117, v240
	s_nop 1
	v_mov_b32_dpp v117, v240 quad_perm:[0,1,2,3] row_mask:0x3 bank_mask:0xf
	s_and_saveexec_b64 s[14:15], s[40:41]
	s_cbranch_execz .LBB0_137
	s_waitcnt lgkmcnt(0)
	v_add_f32_e32 v116, v116, v117
	v_add_f32_e32 v117, v114, v115
	v_lshl_add_u64 v[114:115], v[174:175], 3, s[56:57]
	global_atomic_add_f32 v[114:115], v117, off
	global_atomic_add_f32 v[114:115], v116, off offset:4
; DI u32x4 pack8(f32x4 a, f32x4 b) { u32x4 w; w.x = pk2(a[0], a[1]); w.y = pk2(a[2], a[3]); w.z = pk2(b[0], b[1]); w.w = pk2(b[2], b[3]); return w; }
;     DI void operator()(AccRef acc, const Unit& u, int wr, int wc, int fr, int fq) const {
;     ...
;         for (int it = 0; it < 8; ++it) { const int ai = it >> 2, m = it & 3, cur = it & 1;
;             if (it + 1 < 8) { int rn_ = row0 + ((it + 1) >> 2) * 128 + ((it + 1) & 3) * 16; asm volatile("" : "+v"(rn_) :: "memory"); const size_t on = (size_t)rn_ * DM + c0;
; #pragma unroll
;                 for (int bj = 0; bj < 2; ++bj)
; #pragma unroll
;                     for (int n = 0; n < 2; ++n) xb[cur ^ 1][bj][n] = *(const f32x4*)(X + on + bj * 128 + 4 * n); }
;             int row_ = row0 + ai * 128 + m * 16; asm volatile("" : "+v"(row_)); const size_t off = (size_t)row_ * DM + c0; float s1 = 0.f, s2 = 0.f;
; #pragma unroll
;             for (int bj = 0; bj < 2; ++bj) { f32x4 y[2];
; #pragma unroll
;                 for (int n = 0; n < 2; ++n) { y[n] = xb[cur][bj][n] * ALPHA + acc[ai][bj][m][n]; *(f32x4*)(Y + off + bj * 128 + 4 * n) = y[n];
;                     s1 += (y[n][0] + y[n][1]) + (y[n][2] + y[n][3]); s2 += (y[n][0] * y[n][0] + y[n][1] * y[n][1]) + (y[n][2] * y[n][2] + y[n][3] * y[n][3]); }
;                 const f32x4 g0 = *(const f32x4*)(G + c0 + bj * 128), g1 = *(const f32x4*)(G + c0 + bj * 128 + 4);
;                 *(u32x4*)(YG + off + bj * 128) = pack8(y[0] * g0, y[1] * g1); }
;             s1 += __shfl_xor(s1, 16); s1 += __shfl_xor(s1, 32); s2 += __shfl_xor(s2, 16); s2 += __shfl_xor(s2, 32);
;             if (fq == 0) { unsafeAtomicAdd(ST + (size_t)row_ * 2, s1); unsafeAtomicAdd(ST + (size_t)row_ * 2 + 1, s2); } }
.LBB0_137:
	s_or_b64 exec, exec, s[14:15]
	v_or_b32_e32 v150, 32, v184
	v_mov_b32_e32 v114, v150
	v_pk_fma_f32 v[112:113], v[148:149], s[30:31], v[112:113] op_sel_hi:[1,0,1]
	v_ashrrev_i32_e32 v115, 31, v114
	v_lshlrev_b64 v[114:115], 12, v[114:115]
	v_lshl_add_u64 v[114:115], s[10:11], 0, v[114:115]
	v_lshl_add_u64 v[118:119], v[168:169], 2, v[114:115]
	global_load_dwordx4 v[122:125], v[118:119], off offset:16
	global_load_dwordx4 v[126:129], v[118:119], off
	s_waitcnt lgkmcnt(0)
	global_load_dwordx4 v[114:117], v[118:119], off offset:528
	s_nop 0
	global_load_dwordx4 v[118:121], v[118:119], off offset:512
	v_pk_fma_f32 v[110:111], v[146:147], s[30:31], v[110:111] op_sel_hi:[1,0,1]
	v_ashrrev_i32_e32 v173, 31, v172
	v_lshlrev_b64 v[154:155], 10, v[172:173]
	v_lshl_add_u64 v[154:155], v[154:155], 0, v[168:169]
	v_lshl_add_u64 v[156:157], v[154:155], 2, s[60:61]
	v_pk_fma_f32 v[108:109], v[144:145], s[30:31], v[108:109] op_sel_hi:[1,0,1]
	v_pk_fma_f32 v[106:107], v[142:143], s[30:31], v[106:107] op_sel_hi:[1,0,1]
	global_store_dwordx4 v[156:157], v[110:113], off
	global_store_dwordx4 v[156:157], v[106:109], off offset:16
	global_load_dwordx4 v[142:145], v[170:171], off
	global_load_dwordx4 v[146:149], v[170:171], off offset:16
	v_pk_fma_f32 v[104:105], v[140:141], s[30:31], v[104:105] op_sel_hi:[1,0,1]
	v_pk_fma_f32 v[102:103], v[138:139], s[30:31], v[102:103] op_sel_hi:[1,0,1]
	v_pk_fma_f32 v[136:137], v[136:137], s[30:31], v[100:101] op_sel_hi:[1,0,1]
	v_pk_fma_f32 v[134:135], v[134:135], s[30:31], v[98:99] op_sel_hi:[1,0,1]
	v_lshl_add_u64 v[154:155], v[154:155], 1, s[58:59]
	v_mul_f32_e32 v174, v136, v136
	v_add_f32_e32 v151, v134, v135
	v_fmac_f32_e32 v174, v137, v137
	s_waitcnt vmcnt(0)
	v_pk_mul_f32 v[100:101], v[112:113], v[144:145]
	v_pk_mul_f32 v[98:99], v[110:111], v[142:143]
	v_pk_mul_f32 v[138:139], v[108:109], v[148:149]
	v_pk_mul_f32 v[140:141], v[106:107], v[146:147]
	v_cvt_pk_bf16_f32 v98, v98, v99
	v_cvt_pk_bf16_f32 v99, v100, v101
	v_cvt_pk_bf16_f32 v100, v140, v141
	v_cvt_pk_bf16_f32 v101, v138, v139
	global_store_dwordx4 v[154:155], v[98:101], off
	global_store_dwordx4 v[156:157], v[102:105], off offset:512
	global_store_dwordx4 v[156:157], v[134:137], off offset:528
	global_load_dwordx4 v[138:141], v[170:171], off offset:512
	global_load_dwordx4 v[142:145], v[170:171], off offset:528
	v_add_f32_e32 v98, v110, v111
	v_add_f32_e32 v99, v113, v112
	v_mul_f32_e32 v100, v111, v111
	v_mul_f32_e32 v101, v112, v112
	v_add_f32_e32 v111, v106, v107
	v_add_f32_e32 v112, v109, v108
	v_mul_f32_e32 v107, v107, v107
	v_mul_f32_e32 v108, v108, v108
	v_mul_f32_e32 v148, v103, v103
	v_mul_f32_e32 v149, v104, v104
	v_add_f32_e32 v98, v98, v99
	v_fmac_f32_e32 v100, v110, v110
	v_fmac_f32_e32 v101, v113, v113
	v_fmac_f32_e32 v107, v106, v106
	v_fmac_f32_e32 v108, v109, v109
	v_add_f32_e32 v146, v102, v103
	v_add_f32_e32 v147, v105, v104
	v_mul_f32_e32 v157, v135, v135
	v_add_f32_e32 v99, v111, v112
	v_fmac_f32_e32 v148, v102, v102
	v_fmac_f32_e32 v149, v105, v105
	v_add_f32_e32 v98, 0, v98
	v_add_f32_e32 v100, v100, v101
	v_add_f32_e32 v101, v107, v108
	v_add_f32_e32 v156, v137, v136
	v_add_f32_e32 v106, v146, v147
	v_fmac_f32_e32 v157, v134, v134
	v_add_f32_e32 v107, v148, v149
	v_add_f32_e32 v98, v98, v99
	v_add_f32_e32 v99, v100, v101
	v_add_f32_e32 v109, v151, v156
	v_add_f32_e32 v108, v157, v174
	v_add_f32_e32 v98, v98, v106
	v_add_f32_e32 v99, v99, v107
	v_add_f32_e32 v98, v98, v109
	v_add_f32_e32 v99, v99, v108
	v_mov_b32_e32 v100, v98
	v_mov_b32_e32 v240, v98
	s_nop 1
	v_permlane16_swap_b32_e32 v100, v240
	s_nop 1
	v_mov_b32_dpp v100, v240 quad_perm:[0,1,2,3] row_mask:0x5 bank_mask:0xf
	v_mov_b32_e32 v101, v99
	v_mov_b32_e32 v240, v99
	s_nop 1
	v_permlane16_swap_b32_e32 v101, v240
	s_nop 1
	v_mov_b32_dpp v101, v240 quad_perm:[0,1,2,3] row_mask:0x5 bank_mask:0xf
	s_waitcnt lgkmcnt(0)
	v_add_f32_e32 v98, v98, v100
	v_add_f32_e32 v100, v99, v101
	v_mov_b32_e32 v99, v98
	v_mov_b32_e32 v240, v98
	s_nop 1
	v_permlane32_swap_b32_e32 v99, v240
	s_nop 1
	v_mov_b32_dpp v99, v240 quad_perm:[0,1,2,3] row_mask:0x3 bank_mask:0xf
	v_mov_b32_e32 v101, v100
	v_mov_b32_e32 v240, v100
	s_nop 1
	v_permlane32_swap_b32_e32 v101, v240
	s_nop 1
	v_mov_b32_dpp v101, v240 quad_perm:[0,1,2,3] row_mask:0x3 bank_mask:0xf
	s_waitcnt vmcnt(0)
	v_pk_mul_f32 v[104:105], v[104:105], v[140:141]
	v_pk_mul_f32 v[102:103], v[102:103], v[138:139]
	v_pk_mul_f32 v[106:107], v[136:137], v[144:145]
	v_pk_mul_f32 v[108:109], v[134:135], v[142:143]
	v_cvt_pk_bf16_f32 v102, v102, v103
	v_cvt_pk_bf16_f32 v103, v104, v105
	v_cvt_pk_bf16_f32 v104, v108, v109
	v_cvt_pk_bf16_f32 v105, v106, v107
	global_store_dwordx4 v[154:155], v[102:105], off offset:256
	s_and_saveexec_b64 s[14:15], s[40:41]
	s_cbranch_execz .LBB0_139
	s_waitcnt lgkmcnt(0)
	v_add_f32_e32 v100, v100, v101
	v_add_f32_e32 v101, v98, v99
	v_lshl_add_u64 v[98:99], v[172:173], 3, s[56:57]
	global_atomic_add_f32 v[98:99], v101, off
	global_atomic_add_f32 v[98:99], v100, off offset:4
; DI u32x4 pack8(f32x4 a, f32x4 b) { u32x4 w; w.x = pk2(a[0], a[1]); w.y = pk2(a[2], a[3]); w.z = pk2(b[0], b[1]); w.w = pk2(b[2], b[3]); return w; }
;     DI void operator()(AccRef acc, const Unit& u, int wr, int wc, int fr, int fq) const {
;     ...
;         for (int it = 0; it < 8; ++it) { const int ai = it >> 2, m = it & 3, cur = it & 1;
;             if (it + 1 < 8) { int rn_ = row0 + ((it + 1) >> 2) * 128 + ((it + 1) & 3) * 16; asm volatile("" : "+v"(rn_) :: "memory"); const size_t on = (size_t)rn_ * DM + c0;
; #pragma unroll
;                 for (int bj = 0; bj < 2; ++bj)
; #pragma unroll
;                     for (int n = 0; n < 2; ++n) xb[cur ^ 1][bj][n] = *(const f32x4*)(X + on + bj * 128 + 4 * n); }
;             int row_ = row0 + ai * 128 + m * 16; asm volatile("" : "+v"(row_)); const size_t off = (size_t)row_ * DM + c0; float s1 = 0.f, s2 = 0.f;
; #pragma unroll
;             for (int bj = 0; bj < 2; ++bj) { f32x4 y[2];
; #pragma unroll
;                 for (int n = 0; n < 2; ++n) { y[n] = xb[cur][bj][n] * ALPHA + acc[ai][bj][m][n]; *(f32x4*)(Y + off + bj * 128 + 4 * n) = y[n];
;                     s1 += (y[n][0] + y[n][1]) + (y[n][2] + y[n][3]); s2 += (y[n][0] * y[n][0] + y[n][1] * y[n][1]) + (y[n][2] * y[n][2] + y[n][3] * y[n][3]); }
;                 const f32x4 g0 = *(const f32x4*)(G + c0 + bj * 128), g1 = *(const f32x4*)(G + c0 + bj * 128 + 4);
;                 *(u32x4*)(YG + off + bj * 128) = pack8(y[0] * g0, y[1] * g1); }
;             s1 += __shfl_xor(s1, 16); s1 += __shfl_xor(s1, 32); s2 += __shfl_xor(s2, 16); s2 += __shfl_xor(s2, 32);
;             if (fq == 0) { unsafeAtomicAdd(ST + (size_t)row_ * 2, s1); unsafeAtomicAdd(ST + (size_t)row_ * 2 + 1, s2); } }
.LBB0_139:
	s_or_b64 exec, exec, s[14:15]
	v_or_b32_e32 v134, 48, v184
	v_mov_b32_e32 v98, v134
	v_pk_fma_f32 v[96:97], v[128:129], s[30:31], v[96:97] op_sel_hi:[1,0,1]
	s_waitcnt lgkmcnt(0)
	v_ashrrev_i32_e32 v99, 31, v98
	v_lshlrev_b64 v[98:99], 12, v[98:99]
	v_lshl_add_u64 v[98:99], s[10:11], 0, v[98:99]
	v_lshl_add_u64 v[102:103], v[168:169], 2, v[98:99]
	global_load_dwordx4 v[106:109], v[102:103], off offset:16
	global_load_dwordx4 v[110:113], v[102:103], off
	global_load_dwordx4 v[98:101], v[102:103], off offset:528
	s_nop 0
	global_load_dwordx4 v[102:105], v[102:103], off offset:512
	v_pk_fma_f32 v[94:95], v[126:127], s[30:31], v[94:95] op_sel_hi:[1,0,1]
	v_ashrrev_i32_e32 v151, 31, v150
	v_lshlrev_b64 v[136:137], 10, v[150:151]
	v_lshl_add_u64 v[136:137], v[136:137], 0, v[168:169]
	v_lshl_add_u64 v[138:139], v[136:137], 2, s[60:61]
	v_pk_fma_f32 v[92:93], v[124:125], s[30:31], v[92:93] op_sel_hi:[1,0,1]
	v_pk_fma_f32 v[90:91], v[122:123], s[30:31], v[90:91] op_sel_hi:[1,0,1]
	global_store_dwordx4 v[138:139], v[94:97], off
	global_store_dwordx4 v[138:139], v[90:93], off offset:16
	global_load_dwordx4 v[122:125], v[170:171], off
	global_load_dwordx4 v[126:129], v[170:171], off offset:16
	v_pk_fma_f32 v[88:89], v[120:121], s[30:31], v[88:89] op_sel_hi:[1,0,1]
	v_pk_fma_f32 v[86:87], v[118:119], s[30:31], v[86:87] op_sel_hi:[1,0,1]
	v_pk_fma_f32 v[116:117], v[116:117], s[30:31], v[84:85] op_sel_hi:[1,0,1]
	v_pk_fma_f32 v[114:115], v[114:115], s[30:31], v[82:83] op_sel_hi:[1,0,1]
	v_lshl_add_u64 v[136:137], v[136:137], 1, s[58:59]
	v_mul_f32_e32 v140, v116, v116
	v_add_f32_e32 v135, v114, v115
	v_fmac_f32_e32 v140, v117, v117
	s_waitcnt vmcnt(0)
	v_pk_mul_f32 v[84:85], v[96:97], v[124:125]
	v_pk_mul_f32 v[82:83], v[94:95], v[122:123]
	v_pk_mul_f32 v[118:119], v[92:93], v[128:129]
	v_pk_mul_f32 v[120:121], v[90:91], v[126:127]
	v_cvt_pk_bf16_f32 v82, v82, v83
	v_cvt_pk_bf16_f32 v83, v84, v85
	v_cvt_pk_bf16_f32 v84, v120, v121
	v_cvt_pk_bf16_f32 v85, v118, v119
	global_store_dwordx4 v[136:137], v[82:85], off
	global_store_dwordx4 v[138:139], v[86:89], off offset:512
	global_store_dwordx4 v[138:139], v[114:117], off offset:528
	global_load_dwordx4 v[118:121], v[170:171], off offset:512
	global_load_dwordx4 v[122:125], v[170:171], off offset:528
	v_add_f32_e32 v82, v94, v95
	v_add_f32_e32 v83, v97, v96
	v_mul_f32_e32 v84, v95, v95
	v_mul_f32_e32 v85, v96, v96
	v_add_f32_e32 v95, v90, v91
	v_add_f32_e32 v96, v93, v92
	v_mul_f32_e32 v91, v91, v91
	v_mul_f32_e32 v92, v92, v92
	v_mul_f32_e32 v128, v87, v87
	v_mul_f32_e32 v129, v88, v88
	v_add_f32_e32 v82, v82, v83
	v_fmac_f32_e32 v84, v94, v94
	v_fmac_f32_e32 v85, v97, v97
	v_fmac_f32_e32 v91, v90, v90
	v_fmac_f32_e32 v92, v93, v93
	v_add_f32_e32 v126, v86, v87
	v_add_f32_e32 v127, v89, v88
	v_mul_f32_e32 v139, v115, v115
	v_add_f32_e32 v83, v95, v96
	v_fmac_f32_e32 v128, v86, v86
	v_fmac_f32_e32 v129, v89, v89
	v_add_f32_e32 v82, 0, v82
	v_add_f32_e32 v84, v84, v85
	v_add_f32_e32 v85, v91, v92
	v_add_f32_e32 v138, v117, v116
	v_add_f32_e32 v90, v126, v127
	v_fmac_f32_e32 v139, v114, v114
	v_add_f32_e32 v91, v128, v129
	v_add_f32_e32 v82, v82, v83
	v_add_f32_e32 v83, v84, v85
	v_add_f32_e32 v93, v135, v138
	v_add_f32_e32 v92, v139, v140
	v_add_f32_e32 v82, v82, v90
	v_add_f32_e32 v83, v83, v91
	v_add_f32_e32 v82, v82, v93
	v_add_f32_e32 v83, v83, v92
	v_mov_b32_e32 v84, v82
	v_mov_b32_e32 v240, v82
	s_nop 1
	v_permlane16_swap_b32_e32 v84, v240
	s_nop 1
	v_mov_b32_dpp v84, v240 quad_perm:[0,1,2,3] row_mask:0x5 bank_mask:0xf
	v_mov_b32_e32 v85, v83
	v_mov_b32_e32 v240, v83
	s_nop 1
	v_permlane16_swap_b32_e32 v85, v240
	s_nop 1
	v_mov_b32_dpp v85, v240 quad_perm:[0,1,2,3] row_mask:0x5 bank_mask:0xf
	s_waitcnt lgkmcnt(0)
	v_add_f32_e32 v82, v82, v84
	v_add_f32_e32 v84, v83, v85
	v_mov_b32_e32 v83, v82
	v_mov_b32_e32 v240, v82
	s_nop 1
	v_permlane32_swap_b32_e32 v83, v240
	s_nop 1
	v_mov_b32_dpp v83, v240 quad_perm:[0,1,2,3] row_mask:0x3 bank_mask:0xf
	v_mov_b32_e32 v85, v84
	v_mov_b32_e32 v240, v84
	s_nop 1
	v_permlane32_swap_b32_e32 v85, v240
	s_nop 1
	v_mov_b32_dpp v85, v240 quad_perm:[0,1,2,3] row_mask:0x3 bank_mask:0xf
	s_waitcnt vmcnt(0)
	v_pk_mul_f32 v[88:89], v[88:89], v[120:121]
	v_pk_mul_f32 v[86:87], v[86:87], v[118:119]
	v_pk_mul_f32 v[90:91], v[116:117], v[124:125]
	v_pk_mul_f32 v[92:93], v[114:115], v[122:123]
	v_cvt_pk_bf16_f32 v86, v86, v87
	v_cvt_pk_bf16_f32 v87, v88, v89
	v_cvt_pk_bf16_f32 v88, v92, v93
	v_cvt_pk_bf16_f32 v89, v90, v91
	global_store_dwordx4 v[136:137], v[86:89], off offset:256
	s_and_saveexec_b64 s[14:15], s[40:41]
	s_cbranch_execz .LBB0_141
	s_waitcnt lgkmcnt(0)
	v_add_f32_e32 v84, v84, v85
	v_add_f32_e32 v85, v82, v83
	v_lshl_add_u64 v[82:83], v[150:151], 3, s[56:57]
	global_atomic_add_f32 v[82:83], v85, off
	global_atomic_add_f32 v[82:83], v84, off offset:4
; DI u32x4 pack8(f32x4 a, f32x4 b) { u32x4 w; w.x = pk2(a[0], a[1]); w.y = pk2(a[2], a[3]); w.z = pk2(b[0], b[1]); w.w = pk2(b[2], b[3]); return w; }
;     DI void operator()(AccRef acc, const Unit& u, int wr, int wc, int fr, int fq) const {
;     ...
;         for (int it = 0; it < 8; ++it) { const int ai = it >> 2, m = it & 3, cur = it & 1;
;             if (it + 1 < 8) { int rn_ = row0 + ((it + 1) >> 2) * 128 + ((it + 1) & 3) * 16; asm volatile("" : "+v"(rn_) :: "memory"); const size_t on = (size_t)rn_ * DM + c0;
; #pragma unroll
;                 for (int bj = 0; bj < 2; ++bj)
; #pragma unroll
;                     for (int n = 0; n < 2; ++n) xb[cur ^ 1][bj][n] = *(const f32x4*)(X + on + bj * 128 + 4 * n); }
;             int row_ = row0 + ai * 128 + m * 16; asm volatile("" : "+v"(row_)); const size_t off = (size_t)row_ * DM + c0; float s1 = 0.f, s2 = 0.f;
; #pragma unroll
;             for (int bj = 0; bj < 2; ++bj) { f32x4 y[2];
; #pragma unroll
;                 for (int n = 0; n < 2; ++n) { y[n] = xb[cur][bj][n] * ALPHA + acc[ai][bj][m][n]; *(f32x4*)(Y + off + bj * 128 + 4 * n) = y[n];
;                     s1 += (y[n][0] + y[n][1]) + (y[n][2] + y[n][3]); s2 += (y[n][0] * y[n][0] + y[n][1] * y[n][1]) + (y[n][2] * y[n][2] + y[n][3] * y[n][3]); }
;                 const f32x4 g0 = *(const f32x4*)(G + c0 + bj * 128), g1 = *(const f32x4*)(G + c0 + bj * 128 + 4);
;                 *(u32x4*)(YG + off + bj * 128) = pack8(y[0] * g0, y[1] * g1); }
;             s1 += __shfl_xor(s1, 16); s1 += __shfl_xor(s1, 32); s2 += __shfl_xor(s2, 16); s2 += __shfl_xor(s2, 32);
;             if (fq == 0) { unsafeAtomicAdd(ST + (size_t)row_ * 2, s1); unsafeAtomicAdd(ST + (size_t)row_ * 2 + 1, s2); } }
.LBB0_141:
	s_or_b64 exec, exec, s[14:15]
	v_add_u32_e32 v114, 0x80, v184
	v_mov_b32_e32 v82, v114
	v_pk_fma_f32 v[80:81], v[112:113], s[30:31], v[80:81] op_sel_hi:[1,0,1]
	s_waitcnt lgkmcnt(0)
	v_ashrrev_i32_e32 v83, 31, v82
	v_lshlrev_b64 v[82:83], 12, v[82:83]
	v_lshl_add_u64 v[82:83], s[10:11], 0, v[82:83]
	v_lshl_add_u64 v[86:87], v[168:169], 2, v[82:83]
	global_load_dwordx4 v[90:93], v[86:87], off offset:16
	global_load_dwordx4 v[94:97], v[86:87], off
	global_load_dwordx4 v[82:85], v[86:87], off offset:528
	s_nop 0
	global_load_dwordx4 v[86:89], v[86:87], off offset:512
	v_pk_fma_f32 v[78:79], v[110:111], s[30:31], v[78:79] op_sel_hi:[1,0,1]
	v_ashrrev_i32_e32 v135, 31, v134
	v_lshlrev_b64 v[116:117], 10, v[134:135]
	v_lshl_add_u64 v[116:117], v[116:117], 0, v[168:169]
	v_lshl_add_u64 v[118:119], v[116:117], 2, s[60:61]
	v_pk_fma_f32 v[76:77], v[108:109], s[30:31], v[76:77] op_sel_hi:[1,0,1]
	v_pk_fma_f32 v[74:75], v[106:107], s[30:31], v[74:75] op_sel_hi:[1,0,1]
	global_store_dwordx4 v[118:119], v[78:81], off
	global_store_dwordx4 v[118:119], v[74:77], off offset:16
	global_load_dwordx4 v[106:109], v[170:171], off
	global_load_dwordx4 v[110:113], v[170:171], off offset:16
	v_pk_fma_f32 v[72:73], v[104:105], s[30:31], v[72:73] op_sel_hi:[1,0,1]
	v_pk_fma_f32 v[70:71], v[102:103], s[30:31], v[70:71] op_sel_hi:[1,0,1]
	v_pk_fma_f32 v[100:101], v[100:101], s[30:31], v[68:69] op_sel_hi:[1,0,1]
	v_pk_fma_f32 v[98:99], v[98:99], s[30:31], v[66:67] op_sel_hi:[1,0,1]
	v_lshl_add_u64 v[116:117], v[116:117], 1, s[58:59]
	v_mul_f32_e32 v120, v100, v100
	v_add_f32_e32 v115, v98, v99
	v_fmac_f32_e32 v120, v101, v101
	s_waitcnt vmcnt(0)
	v_pk_mul_f32 v[68:69], v[80:81], v[108:109]
	v_pk_mul_f32 v[66:67], v[78:79], v[106:107]
	v_pk_mul_f32 v[102:103], v[76:77], v[112:113]
	v_pk_mul_f32 v[104:105], v[74:75], v[110:111]
	v_cvt_pk_bf16_f32 v66, v66, v67
	v_cvt_pk_bf16_f32 v67, v68, v69
	v_cvt_pk_bf16_f32 v68, v104, v105
	v_cvt_pk_bf16_f32 v69, v102, v103
	global_store_dwordx4 v[116:117], v[66:69], off
	global_store_dwordx4 v[118:119], v[70:73], off offset:512
	global_store_dwordx4 v[118:119], v[98:101], off offset:528
	global_load_dwordx4 v[102:105], v[170:171], off offset:512
	global_load_dwordx4 v[106:109], v[170:171], off offset:528
	v_add_f32_e32 v66, v78, v79
	v_add_f32_e32 v67, v81, v80
	v_mul_f32_e32 v68, v79, v79
	v_mul_f32_e32 v69, v80, v80
	v_add_f32_e32 v79, v74, v75
	v_add_f32_e32 v80, v77, v76
	v_mul_f32_e32 v75, v75, v75
	v_mul_f32_e32 v76, v76, v76
	v_mul_f32_e32 v112, v71, v71
	v_mul_f32_e32 v113, v72, v72
	v_add_f32_e32 v66, v66, v67
	v_fmac_f32_e32 v68, v78, v78
	v_fmac_f32_e32 v69, v81, v81
	v_fmac_f32_e32 v75, v74, v74
	v_fmac_f32_e32 v76, v77, v77
	v_add_f32_e32 v110, v70, v71
	v_add_f32_e32 v111, v73, v72
	v_mul_f32_e32 v119, v99, v99
	v_add_f32_e32 v67, v79, v80
	v_fmac_f32_e32 v112, v70, v70
	v_fmac_f32_e32 v113, v73, v73
	v_add_f32_e32 v66, 0, v66
	v_add_f32_e32 v68, v68, v69
	v_add_f32_e32 v69, v75, v76
	v_add_f32_e32 v118, v101, v100
	v_add_f32_e32 v74, v110, v111
	v_fmac_f32_e32 v119, v98, v98
	v_add_f32_e32 v75, v112, v113
	v_add_f32_e32 v66, v66, v67
	v_add_f32_e32 v67, v68, v69
	v_add_f32_e32 v77, v115, v118
	v_add_f32_e32 v76, v119, v120
	v_add_f32_e32 v66, v66, v74
	v_add_f32_e32 v67, v67, v75
	v_add_f32_e32 v66, v66, v77
	v_add_f32_e32 v67, v67, v76
	v_mov_b32_e32 v68, v66
	v_mov_b32_e32 v240, v66
	s_nop 1
	v_permlane16_swap_b32_e32 v68, v240
	s_nop 1
	v_mov_b32_dpp v68, v240 quad_perm:[0,1,2,3] row_mask:0x5 bank_mask:0xf
	v_mov_b32_e32 v69, v67
	v_mov_b32_e32 v240, v67
	s_nop 1
	v_permlane16_swap_b32_e32 v69, v240
	s_nop 1
	v_mov_b32_dpp v69, v240 quad_perm:[0,1,2,3] row_mask:0x5 bank_mask:0xf
	s_waitcnt lgkmcnt(0)
	v_add_f32_e32 v66, v66, v68
	v_add_f32_e32 v68, v67, v69
	v_mov_b32_e32 v67, v66
	v_mov_b32_e32 v240, v66
	s_nop 1
	v_permlane32_swap_b32_e32 v67, v240
	s_nop 1
	v_mov_b32_dpp v67, v240 quad_perm:[0,1,2,3] row_mask:0x3 bank_mask:0xf
	v_mov_b32_e32 v69, v68
	v_mov_b32_e32 v240, v68
	s_nop 1
	v_permlane32_swap_b32_e32 v69, v240
	s_nop 1
	v_mov_b32_dpp v69, v240 quad_perm:[0,1,2,3] row_mask:0x3 bank_mask:0xf
	s_waitcnt vmcnt(0)
	v_pk_mul_f32 v[72:73], v[72:73], v[104:105]
	v_pk_mul_f32 v[70:71], v[70:71], v[102:103]
	v_pk_mul_f32 v[74:75], v[100:101], v[108:109]
	v_pk_mul_f32 v[76:77], v[98:99], v[106:107]
	v_cvt_pk_bf16_f32 v70, v70, v71
	v_cvt_pk_bf16_f32 v71, v72, v73
	v_cvt_pk_bf16_f32 v72, v76, v77
	v_cvt_pk_bf16_f32 v73, v74, v75
	global_store_dwordx4 v[116:117], v[70:73], off offset:256
	s_and_saveexec_b64 s[14:15], s[40:41]
	s_cbranch_execz .LBB0_143
	s_waitcnt lgkmcnt(0)
	v_add_f32_e32 v68, v68, v69
	v_add_f32_e32 v69, v66, v67
	v_lshl_add_u64 v[66:67], v[134:135], 3, s[56:57]
	global_atomic_add_f32 v[66:67], v69, off
	global_atomic_add_f32 v[66:67], v68, off offset:4
; DI u32x4 pack8(f32x4 a, f32x4 b) { u32x4 w; w.x = pk2(a[0], a[1]); w.y = pk2(a[2], a[3]); w.z = pk2(b[0], b[1]); w.w = pk2(b[2], b[3]); return w; }
;     DI void operator()(AccRef acc, const Unit& u, int wr, int wc, int fr, int fq) const {
;     ...
;         for (int it = 0; it < 8; ++it) { const int ai = it >> 2, m = it & 3, cur = it & 1;
;             if (it + 1 < 8) { int rn_ = row0 + ((it + 1) >> 2) * 128 + ((it + 1) & 3) * 16; asm volatile("" : "+v"(rn_) :: "memory"); const size_t on = (size_t)rn_ * DM + c0;
; #pragma unroll
;                 for (int bj = 0; bj < 2; ++bj)
; #pragma unroll
;                     for (int n = 0; n < 2; ++n) xb[cur ^ 1][bj][n] = *(const f32x4*)(X + on + bj * 128 + 4 * n); }
;             int row_ = row0 + ai * 128 + m * 16; asm volatile("" : "+v"(row_)); const size_t off = (size_t)row_ * DM + c0; float s1 = 0.f, s2 = 0.f;
; #pragma unroll
;             for (int bj = 0; bj < 2; ++bj) { f32x4 y[2];
; #pragma unroll
;                 for (int n = 0; n < 2; ++n) { y[n] = xb[cur][bj][n] * ALPHA + acc[ai][bj][m][n]; *(f32x4*)(Y + off + bj * 128 + 4 * n) = y[n];
;                     s1 += (y[n][0] + y[n][1]) + (y[n][2] + y[n][3]); s2 += (y[n][0] * y[n][0] + y[n][1] * y[n][1]) + (y[n][2] * y[n][2] + y[n][3] * y[n][3]); }
;                 const f32x4 g0 = *(const f32x4*)(G + c0 + bj * 128), g1 = *(const f32x4*)(G + c0 + bj * 128 + 4);
;                 *(u32x4*)(YG + off + bj * 128) = pack8(y[0] * g0, y[1] * g1); }
;             s1 += __shfl_xor(s1, 16); s1 += __shfl_xor(s1, 32); s2 += __shfl_xor(s2, 16); s2 += __shfl_xor(s2, 32);
;             if (fq == 0) { unsafeAtomicAdd(ST + (size_t)row_ * 2, s1); unsafeAtomicAdd(ST + (size_t)row_ * 2 + 1, s2); } }
.LBB0_143:
	s_or_b64 exec, exec, s[14:15]
	v_or_b32_e32 v98, 16, v114
	v_mov_b32_e32 v66, v98
	v_mov_b32_e32 v100, v114
	s_waitcnt lgkmcnt(0)
	v_ashrrev_i32_e32 v67, 31, v66
	v_lshlrev_b64 v[66:67], 12, v[66:67]
	v_lshl_add_u64 v[66:67], s[10:11], 0, v[66:67]
	v_lshl_add_u64 v[70:71], v[168:169], 2, v[66:67]
	global_load_dwordx4 v[74:77], v[70:71], off offset:16
	global_load_dwordx4 v[78:81], v[70:71], off
	global_load_dwordx4 v[66:69], v[70:71], off offset:528
	s_nop 0
	global_load_dwordx4 v[70:73], v[70:71], off offset:512
	v_pk_fma_f32 v[64:65], v[96:97], s[30:31], v[64:65] op_sel_hi:[1,0,1]
	v_ashrrev_i32_e32 v101, 31, v100
	v_lshlrev_b64 v[102:103], 10, v[100:101]
	v_lshl_add_u64 v[102:103], v[102:103], 0, v[168:169]
	v_lshl_add_u64 v[104:105], v[102:103], 2, s[60:61]
	v_pk_fma_f32 v[62:63], v[94:95], s[30:31], v[62:63] op_sel_hi:[1,0,1]
	v_pk_fma_f32 v[60:61], v[92:93], s[30:31], v[60:61] op_sel_hi:[1,0,1]
	v_pk_fma_f32 v[58:59], v[90:91], s[30:31], v[58:59] op_sel_hi:[1,0,1]
	global_store_dwordx4 v[104:105], v[62:65], off
	global_store_dwordx4 v[104:105], v[58:61], off offset:16
	global_load_dwordx4 v[90:93], v[170:171], off
	global_load_dwordx4 v[94:97], v[170:171], off offset:16
	v_pk_fma_f32 v[56:57], v[88:89], s[30:31], v[56:57] op_sel_hi:[1,0,1]
	v_pk_fma_f32 v[54:55], v[86:87], s[30:31], v[54:55] op_sel_hi:[1,0,1]
	v_pk_fma_f32 v[84:85], v[84:85], s[30:31], v[52:53] op_sel_hi:[1,0,1]
	v_pk_fma_f32 v[82:83], v[82:83], s[30:31], v[50:51] op_sel_hi:[1,0,1]
	v_lshl_add_u64 v[102:103], v[102:103], 1, s[58:59]
	v_mul_f32_e32 v106, v84, v84
	v_add_f32_e32 v99, v82, v83
	v_fmac_f32_e32 v106, v85, v85
	s_waitcnt vmcnt(0)
	v_pk_mul_f32 v[52:53], v[64:65], v[92:93]
	v_pk_mul_f32 v[50:51], v[62:63], v[90:91]
	v_pk_mul_f32 v[86:87], v[60:61], v[96:97]
	v_pk_mul_f32 v[88:89], v[58:59], v[94:95]
	v_cvt_pk_bf16_f32 v50, v50, v51
	v_cvt_pk_bf16_f32 v51, v52, v53
	v_cvt_pk_bf16_f32 v52, v88, v89
	v_cvt_pk_bf16_f32 v53, v86, v87
	global_store_dwordx4 v[102:103], v[50:53], off
	global_store_dwordx4 v[104:105], v[54:57], off offset:512
	global_store_dwordx4 v[104:105], v[82:85], off offset:528
	global_load_dwordx4 v[86:89], v[170:171], off offset:512
	global_load_dwordx4 v[90:93], v[170:171], off offset:528
	v_add_f32_e32 v50, v62, v63
	v_add_f32_e32 v51, v65, v64
	v_mul_f32_e32 v52, v63, v63
	v_mul_f32_e32 v53, v64, v64
	v_add_f32_e32 v63, v58, v59
	v_add_f32_e32 v64, v61, v60
	v_mul_f32_e32 v59, v59, v59
	v_mul_f32_e32 v60, v60, v60
	v_mul_f32_e32 v96, v55, v55
	v_mul_f32_e32 v97, v56, v56
	v_add_f32_e32 v50, v50, v51
	v_fmac_f32_e32 v52, v62, v62
	v_fmac_f32_e32 v53, v65, v65
	v_fmac_f32_e32 v59, v58, v58
	v_fmac_f32_e32 v60, v61, v61
	v_add_f32_e32 v94, v54, v55
	v_add_f32_e32 v95, v57, v56
	v_mul_f32_e32 v105, v83, v83
	v_add_f32_e32 v51, v63, v64
	v_fmac_f32_e32 v96, v54, v54
	v_fmac_f32_e32 v97, v57, v57
	v_add_f32_e32 v50, 0, v50
	v_add_f32_e32 v52, v52, v53
	v_add_f32_e32 v53, v59, v60
	v_add_f32_e32 v104, v85, v84
	v_add_f32_e32 v58, v94, v95
	v_fmac_f32_e32 v105, v82, v82
	v_add_f32_e32 v59, v96, v97
	v_add_f32_e32 v50, v50, v51
	v_add_f32_e32 v51, v52, v53
	v_add_f32_e32 v61, v99, v104
	v_add_f32_e32 v60, v105, v106
	v_add_f32_e32 v50, v50, v58
	v_add_f32_e32 v51, v51, v59
	v_add_f32_e32 v50, v50, v61
	v_add_f32_e32 v51, v51, v60
	v_mov_b32_e32 v52, v50
	v_mov_b32_e32 v240, v50
	s_nop 1
	v_permlane16_swap_b32_e32 v52, v240
	s_nop 1
	v_mov_b32_dpp v52, v240 quad_perm:[0,1,2,3] row_mask:0x5 bank_mask:0xf
	v_mov_b32_e32 v53, v51
	v_mov_b32_e32 v240, v51
	s_nop 1
	v_permlane16_swap_b32_e32 v53, v240
	s_nop 1
	v_mov_b32_dpp v53, v240 quad_perm:[0,1,2,3] row_mask:0x5 bank_mask:0xf
	s_waitcnt lgkmcnt(0)
	v_add_f32_e32 v50, v50, v52
	v_add_f32_e32 v52, v51, v53
	v_mov_b32_e32 v51, v50
	v_mov_b32_e32 v240, v50
	s_nop 1
	v_permlane32_swap_b32_e32 v51, v240
	s_nop 1
	v_mov_b32_dpp v51, v240 quad_perm:[0,1,2,3] row_mask:0x3 bank_mask:0xf
	v_mov_b32_e32 v53, v52
	v_mov_b32_e32 v240, v52
	s_nop 1
	v_permlane32_swap_b32_e32 v53, v240
	s_nop 1
	v_mov_b32_dpp v53, v240 quad_perm:[0,1,2,3] row_mask:0x3 bank_mask:0xf
	s_waitcnt vmcnt(0)
	v_pk_mul_f32 v[56:57], v[56:57], v[88:89]
	v_pk_mul_f32 v[54:55], v[54:55], v[86:87]
	v_pk_mul_f32 v[58:59], v[84:85], v[92:93]
	v_pk_mul_f32 v[60:61], v[82:83], v[90:91]
	v_cvt_pk_bf16_f32 v54, v54, v55
	v_cvt_pk_bf16_f32 v55, v56, v57
	v_cvt_pk_bf16_f32 v56, v60, v61
	v_cvt_pk_bf16_f32 v57, v58, v59
	global_store_dwordx4 v[102:103], v[54:57], off offset:256
	s_and_saveexec_b64 s[14:15], s[40:41]
	s_cbranch_execz .LBB0_145
	s_waitcnt lgkmcnt(0)
	v_add_f32_e32 v52, v52, v53
	v_add_f32_e32 v53, v50, v51
	v_lshl_add_u64 v[50:51], v[100:101], 3, s[56:57]
	global_atomic_add_f32 v[50:51], v53, off
	global_atomic_add_f32 v[50:51], v52, off offset:4
; DI u32x4 pack8(f32x4 a, f32x4 b) { u32x4 w; w.x = pk2(a[0], a[1]); w.y = pk2(a[2], a[3]); w.z = pk2(b[0], b[1]); w.w = pk2(b[2], b[3]); return w; }
;     DI void operator()(AccRef acc, const Unit& u, int wr, int wc, int fr, int fq) const {
;     ...
;         for (int it = 0; it < 8; ++it) { const int ai = it >> 2, m = it & 3, cur = it & 1;
;             if (it + 1 < 8) { int rn_ = row0 + ((it + 1) >> 2) * 128 + ((it + 1) & 3) * 16; asm volatile("" : "+v"(rn_) :: "memory"); const size_t on = (size_t)rn_ * DM + c0;
; #pragma unroll
;                 for (int bj = 0; bj < 2; ++bj)
; #pragma unroll
;                     for (int n = 0; n < 2; ++n) xb[cur ^ 1][bj][n] = *(const f32x4*)(X + on + bj * 128 + 4 * n); }
;             int row_ = row0 + ai * 128 + m * 16; asm volatile("" : "+v"(row_)); const size_t off = (size_t)row_ * DM + c0; float s1 = 0.f, s2 = 0.f;
; #pragma unroll
;             for (int bj = 0; bj < 2; ++bj) { f32x4 y[2];
; #pragma unroll
;                 for (int n = 0; n < 2; ++n) { y[n] = xb[cur][bj][n] * ALPHA + acc[ai][bj][m][n]; *(f32x4*)(Y + off + bj * 128 + 4 * n) = y[n];
;                     s1 += (y[n][0] + y[n][1]) + (y[n][2] + y[n][3]); s2 += (y[n][0] * y[n][0] + y[n][1] * y[n][1]) + (y[n][2] * y[n][2] + y[n][3] * y[n][3]); }
;                 const f32x4 g0 = *(const f32x4*)(G + c0 + bj * 128), g1 = *(const f32x4*)(G + c0 + bj * 128 + 4);
;                 *(u32x4*)(YG + off + bj * 128) = pack8(y[0] * g0, y[1] * g1); }
;             s1 += __shfl_xor(s1, 16); s1 += __shfl_xor(s1, 32); s2 += __shfl_xor(s2, 16); s2 += __shfl_xor(s2, 32);
;             if (fq == 0) { unsafeAtomicAdd(ST + (size_t)row_ * 2, s1); unsafeAtomicAdd(ST + (size_t)row_ * 2 + 1, s2); } }
.LBB0_145:
	s_or_b64 exec, exec, s[14:15]
	v_or_b32_e32 v82, 32, v114
	v_mov_b32_e32 v50, v82
	v_pk_fma_f32 v[48:49], v[80:81], s[30:31], v[48:49] op_sel_hi:[1,0,1]
	s_waitcnt lgkmcnt(0)
	v_ashrrev_i32_e32 v51, 31, v50
	v_lshlrev_b64 v[50:51], 12, v[50:51]
	v_lshl_add_u64 v[50:51], s[10:11], 0, v[50:51]
	v_lshl_add_u64 v[54:55], v[168:169], 2, v[50:51]
	global_load_dwordx4 v[58:61], v[54:55], off offset:16
	global_load_dwordx4 v[62:65], v[54:55], off
	global_load_dwordx4 v[50:53], v[54:55], off offset:528
	s_nop 0
	global_load_dwordx4 v[54:57], v[54:55], off offset:512
	v_pk_fma_f32 v[46:47], v[78:79], s[30:31], v[46:47] op_sel_hi:[1,0,1]
	v_ashrrev_i32_e32 v99, 31, v98
	v_lshlrev_b64 v[84:85], 10, v[98:99]
	v_lshl_add_u64 v[84:85], v[84:85], 0, v[168:169]
	v_lshl_add_u64 v[86:87], v[84:85], 2, s[60:61]
	v_pk_fma_f32 v[44:45], v[76:77], s[30:31], v[44:45] op_sel_hi:[1,0,1]
	v_pk_fma_f32 v[42:43], v[74:75], s[30:31], v[42:43] op_sel_hi:[1,0,1]
	global_store_dwordx4 v[86:87], v[46:49], off
	global_store_dwordx4 v[86:87], v[42:45], off offset:16
	global_load_dwordx4 v[74:77], v[170:171], off
	global_load_dwordx4 v[78:81], v[170:171], off offset:16
	v_pk_fma_f32 v[40:41], v[72:73], s[30:31], v[40:41] op_sel_hi:[1,0,1]
	v_pk_fma_f32 v[38:39], v[70:71], s[30:31], v[38:39] op_sel_hi:[1,0,1]
	v_pk_fma_f32 v[68:69], v[68:69], s[30:31], v[36:37] op_sel_hi:[1,0,1]
	v_pk_fma_f32 v[66:67], v[66:67], s[30:31], v[34:35] op_sel_hi:[1,0,1]
	v_lshl_add_u64 v[84:85], v[84:85], 1, s[58:59]
	v_mul_f32_e32 v88, v68, v68
	v_add_f32_e32 v83, v66, v67
	v_fmac_f32_e32 v88, v69, v69
	s_waitcnt vmcnt(0)
	v_pk_mul_f32 v[36:37], v[48:49], v[76:77]
	v_pk_mul_f32 v[34:35], v[46:47], v[74:75]
	v_pk_mul_f32 v[70:71], v[44:45], v[80:81]
	v_pk_mul_f32 v[72:73], v[42:43], v[78:79]
	v_cvt_pk_bf16_f32 v34, v34, v35
	v_cvt_pk_bf16_f32 v35, v36, v37
	v_cvt_pk_bf16_f32 v36, v72, v73
	v_cvt_pk_bf16_f32 v37, v70, v71
	global_store_dwordx4 v[84:85], v[34:37], off
	global_store_dwordx4 v[86:87], v[38:41], off offset:512
	global_store_dwordx4 v[86:87], v[66:69], off offset:528
	global_load_dwordx4 v[70:73], v[170:171], off offset:512
	global_load_dwordx4 v[74:77], v[170:171], off offset:528
	v_add_f32_e32 v34, v46, v47
	v_add_f32_e32 v35, v49, v48
	v_mul_f32_e32 v36, v47, v47
	v_mul_f32_e32 v37, v48, v48
	v_add_f32_e32 v47, v42, v43
	v_add_f32_e32 v48, v45, v44
	v_mul_f32_e32 v43, v43, v43
	v_mul_f32_e32 v44, v44, v44
	v_mul_f32_e32 v80, v39, v39
	v_mul_f32_e32 v81, v40, v40
	v_add_f32_e32 v34, v34, v35
	v_fmac_f32_e32 v36, v46, v46
	v_fmac_f32_e32 v37, v49, v49
	v_fmac_f32_e32 v43, v42, v42
	v_fmac_f32_e32 v44, v45, v45
	v_add_f32_e32 v78, v38, v39
	v_add_f32_e32 v79, v41, v40
	v_mul_f32_e32 v87, v67, v67
	v_add_f32_e32 v35, v47, v48
	v_fmac_f32_e32 v80, v38, v38
	v_fmac_f32_e32 v81, v41, v41
	v_add_f32_e32 v34, 0, v34
	v_add_f32_e32 v36, v36, v37
	v_add_f32_e32 v37, v43, v44
	v_add_f32_e32 v86, v69, v68
	v_add_f32_e32 v42, v78, v79
	v_fmac_f32_e32 v87, v66, v66
	v_add_f32_e32 v43, v80, v81
	v_add_f32_e32 v34, v34, v35
	v_add_f32_e32 v35, v36, v37
	v_add_f32_e32 v45, v83, v86
	v_add_f32_e32 v44, v87, v88
	v_add_f32_e32 v34, v34, v42
	v_add_f32_e32 v35, v35, v43
	v_add_f32_e32 v34, v34, v45
	v_add_f32_e32 v35, v35, v44
	v_mov_b32_e32 v36, v34
	v_mov_b32_e32 v240, v34
	s_nop 1
	v_permlane16_swap_b32_e32 v36, v240
	s_nop 1
	v_mov_b32_dpp v36, v240 quad_perm:[0,1,2,3] row_mask:0x5 bank_mask:0xf
	v_mov_b32_e32 v37, v35
	v_mov_b32_e32 v240, v35
	s_nop 1
	v_permlane16_swap_b32_e32 v37, v240
	s_nop 1
	v_mov_b32_dpp v37, v240 quad_perm:[0,1,2,3] row_mask:0x5 bank_mask:0xf
	s_waitcnt lgkmcnt(0)
	v_add_f32_e32 v34, v34, v36
	v_add_f32_e32 v36, v35, v37
	v_mov_b32_e32 v35, v34
	v_mov_b32_e32 v240, v34
	s_nop 1
	v_permlane32_swap_b32_e32 v35, v240
	s_nop 1
	v_mov_b32_dpp v35, v240 quad_perm:[0,1,2,3] row_mask:0x3 bank_mask:0xf
	v_mov_b32_e32 v37, v36
	v_mov_b32_e32 v240, v36
	s_nop 1
	v_permlane32_swap_b32_e32 v37, v240
	s_nop 1
	v_mov_b32_dpp v37, v240 quad_perm:[0,1,2,3] row_mask:0x3 bank_mask:0xf
	s_waitcnt vmcnt(0)
	v_pk_mul_f32 v[40:41], v[40:41], v[72:73]
	v_pk_mul_f32 v[38:39], v[38:39], v[70:71]
	v_pk_mul_f32 v[42:43], v[68:69], v[76:77]
	v_pk_mul_f32 v[44:45], v[66:67], v[74:75]
	v_cvt_pk_bf16_f32 v38, v38, v39
	v_cvt_pk_bf16_f32 v39, v40, v41
	v_cvt_pk_bf16_f32 v40, v44, v45
	v_cvt_pk_bf16_f32 v41, v42, v43
	global_store_dwordx4 v[84:85], v[38:41], off offset:256
	s_and_saveexec_b64 s[14:15], s[40:41]
	s_cbranch_execz .LBB0_147
	s_waitcnt lgkmcnt(0)
	v_add_f32_e32 v36, v36, v37
	v_add_f32_e32 v37, v34, v35
	v_lshl_add_u64 v[34:35], v[98:99], 3, s[56:57]
	global_atomic_add_f32 v[34:35], v37, off
	global_atomic_add_f32 v[34:35], v36, off offset:4
; DI u32x4 pack8(f32x4 a, f32x4 b) { u32x4 w; w.x = pk2(a[0], a[1]); w.y = pk2(a[2], a[3]); w.z = pk2(b[0], b[1]); w.w = pk2(b[2], b[3]); return w; }
;     DI void operator()(AccRef acc, const Unit& u, int wr, int wc, int fr, int fq) const {
;     ...
;         for (int it = 0; it < 8; ++it) { const int ai = it >> 2, m = it & 3, cur = it & 1;
;             if (it + 1 < 8) { int rn_ = row0 + ((it + 1) >> 2) * 128 + ((it + 1) & 3) * 16; asm volatile("" : "+v"(rn_) :: "memory"); const size_t on = (size_t)rn_ * DM + c0;
; #pragma unroll
;                 for (int bj = 0; bj < 2; ++bj)
; #pragma unroll
;                     for (int n = 0; n < 2; ++n) xb[cur ^ 1][bj][n] = *(const f32x4*)(X + on + bj * 128 + 4 * n); }
;             int row_ = row0 + ai * 128 + m * 16; asm volatile("" : "+v"(row_)); const size_t off = (size_t)row_ * DM + c0; float s1 = 0.f, s2 = 0.f;
; #pragma unroll
;             for (int bj = 0; bj < 2; ++bj) { f32x4 y[2];
; #pragma unroll
;                 for (int n = 0; n < 2; ++n) { y[n] = xb[cur][bj][n] * ALPHA + acc[ai][bj][m][n]; *(f32x4*)(Y + off + bj * 128 + 4 * n) = y[n];
;                     s1 += (y[n][0] + y[n][1]) + (y[n][2] + y[n][3]); s2 += (y[n][0] * y[n][0] + y[n][1] * y[n][1]) + (y[n][2] * y[n][2] + y[n][3] * y[n][3]); }
;                 const f32x4 g0 = *(const f32x4*)(G + c0 + bj * 128), g1 = *(const f32x4*)(G + c0 + bj * 128 + 4);
;                 *(u32x4*)(YG + off + bj * 128) = pack8(y[0] * g0, y[1] * g1); }
;             s1 += __shfl_xor(s1, 16); s1 += __shfl_xor(s1, 32); s2 += __shfl_xor(s2, 16); s2 += __shfl_xor(s2, 32);
;             if (fq == 0) { unsafeAtomicAdd(ST + (size_t)row_ * 2, s1); unsafeAtomicAdd(ST + (size_t)row_ * 2 + 1, s2); } }
.LBB0_147:
	s_or_b64 exec, exec, s[14:15]
	v_or_b32_e32 v66, 48, v114
	v_mov_b32_e32 v34, v66
	v_pk_fma_f32 v[32:33], v[64:65], s[30:31], v[32:33] op_sel_hi:[1,0,1]
	s_waitcnt lgkmcnt(0)
	v_ashrrev_i32_e32 v35, 31, v34
	v_lshlrev_b64 v[34:35], 12, v[34:35]
	v_lshl_add_u64 v[34:35], s[10:11], 0, v[34:35]
	v_lshl_add_u64 v[38:39], v[168:169], 2, v[34:35]
	global_load_dwordx4 v[42:45], v[38:39], off offset:16
	global_load_dwordx4 v[46:49], v[38:39], off
	global_load_dwordx4 v[34:37], v[38:39], off offset:528
	s_nop 0
	global_load_dwordx4 v[38:41], v[38:39], off offset:512
	v_pk_fma_f32 v[30:31], v[62:63], s[30:31], v[30:31] op_sel_hi:[1,0,1]
	v_ashrrev_i32_e32 v83, 31, v82
	v_lshlrev_b64 v[68:69], 10, v[82:83]
	v_lshl_add_u64 v[68:69], v[68:69], 0, v[168:169]
	v_lshl_add_u64 v[70:71], v[68:69], 2, s[60:61]
	v_pk_fma_f32 v[28:29], v[60:61], s[30:31], v[28:29] op_sel_hi:[1,0,1]
	v_pk_fma_f32 v[26:27], v[58:59], s[30:31], v[26:27] op_sel_hi:[1,0,1]
	global_store_dwordx4 v[70:71], v[30:33], off
	global_store_dwordx4 v[70:71], v[26:29], off offset:16
	global_load_dwordx4 v[58:61], v[170:171], off
	global_load_dwordx4 v[62:65], v[170:171], off offset:16
	v_pk_fma_f32 v[24:25], v[56:57], s[30:31], v[24:25] op_sel_hi:[1,0,1]
	v_pk_fma_f32 v[22:23], v[54:55], s[30:31], v[22:23] op_sel_hi:[1,0,1]
	v_pk_fma_f32 v[52:53], v[52:53], s[30:31], v[20:21] op_sel_hi:[1,0,1]
	v_pk_fma_f32 v[50:51], v[50:51], s[30:31], v[18:19] op_sel_hi:[1,0,1]
	v_lshl_add_u64 v[68:69], v[68:69], 1, s[58:59]
	v_mul_f32_e32 v72, v52, v52
	v_add_f32_e32 v67, v50, v51
	v_fmac_f32_e32 v72, v53, v53
	s_waitcnt vmcnt(0)
	v_pk_mul_f32 v[20:21], v[32:33], v[60:61]
	v_pk_mul_f32 v[18:19], v[30:31], v[58:59]
	v_pk_mul_f32 v[54:55], v[28:29], v[64:65]
	v_pk_mul_f32 v[56:57], v[26:27], v[62:63]
	v_cvt_pk_bf16_f32 v18, v18, v19
	v_cvt_pk_bf16_f32 v19, v20, v21
	v_cvt_pk_bf16_f32 v20, v56, v57
	v_cvt_pk_bf16_f32 v21, v54, v55
	global_store_dwordx4 v[68:69], v[18:21], off
	global_store_dwordx4 v[70:71], v[22:25], off offset:512
	global_store_dwordx4 v[70:71], v[50:53], off offset:528
	global_load_dwordx4 v[54:57], v[170:171], off offset:512
	global_load_dwordx4 v[58:61], v[170:171], off offset:528
	v_add_f32_e32 v18, v30, v31
	v_add_f32_e32 v19, v33, v32
	v_mul_f32_e32 v20, v31, v31
	v_mul_f32_e32 v21, v32, v32
	v_add_f32_e32 v31, v26, v27
	v_add_f32_e32 v32, v29, v28
	v_mul_f32_e32 v27, v27, v27
	v_mul_f32_e32 v28, v28, v28
	v_mul_f32_e32 v64, v23, v23
	v_mul_f32_e32 v65, v24, v24
	v_add_f32_e32 v18, v18, v19
	v_fmac_f32_e32 v20, v30, v30
	v_fmac_f32_e32 v21, v33, v33
	v_fmac_f32_e32 v27, v26, v26
	v_fmac_f32_e32 v28, v29, v29
	v_add_f32_e32 v62, v22, v23
	v_add_f32_e32 v63, v25, v24
	v_mul_f32_e32 v71, v51, v51
	v_add_f32_e32 v19, v31, v32
	v_fmac_f32_e32 v64, v22, v22
	v_fmac_f32_e32 v65, v25, v25
	v_add_f32_e32 v18, 0, v18
	v_add_f32_e32 v20, v20, v21
	v_add_f32_e32 v21, v27, v28
	v_add_f32_e32 v70, v53, v52
	v_add_f32_e32 v26, v62, v63
	v_fmac_f32_e32 v71, v50, v50
	v_add_f32_e32 v27, v64, v65
	v_add_f32_e32 v18, v18, v19
	v_add_f32_e32 v19, v20, v21
	v_add_f32_e32 v29, v67, v70
	v_add_f32_e32 v28, v71, v72
	v_add_f32_e32 v18, v18, v26
	v_add_f32_e32 v19, v19, v27
	v_add_f32_e32 v18, v18, v29
	v_add_f32_e32 v19, v19, v28
	v_mov_b32_e32 v20, v18
	v_mov_b32_e32 v240, v18
	s_nop 1
	v_permlane16_swap_b32_e32 v20, v240
	s_nop 1
	v_mov_b32_dpp v20, v240 quad_perm:[0,1,2,3] row_mask:0x5 bank_mask:0xf
	v_mov_b32_e32 v21, v19
	v_mov_b32_e32 v240, v19
	s_nop 1
	v_permlane16_swap_b32_e32 v21, v240
	s_nop 1
	v_mov_b32_dpp v21, v240 quad_perm:[0,1,2,3] row_mask:0x5 bank_mask:0xf
	s_waitcnt lgkmcnt(0)
	v_add_f32_e32 v18, v18, v20
	v_add_f32_e32 v20, v19, v21
	v_mov_b32_e32 v19, v18
	v_mov_b32_e32 v240, v18
	s_nop 1
	v_permlane32_swap_b32_e32 v19, v240
	s_nop 1
	v_mov_b32_dpp v19, v240 quad_perm:[0,1,2,3] row_mask:0x3 bank_mask:0xf
	v_mov_b32_e32 v21, v20
	v_mov_b32_e32 v240, v20
	s_nop 1
	v_permlane32_swap_b32_e32 v21, v240
	s_nop 1
	v_mov_b32_dpp v21, v240 quad_perm:[0,1,2,3] row_mask:0x3 bank_mask:0xf
	s_waitcnt vmcnt(0)
	v_pk_mul_f32 v[24:25], v[24:25], v[56:57]
	v_pk_mul_f32 v[22:23], v[22:23], v[54:55]
	v_pk_mul_f32 v[26:27], v[52:53], v[60:61]
	v_pk_mul_f32 v[28:29], v[50:51], v[58:59]
	v_cvt_pk_bf16_f32 v22, v22, v23
	v_cvt_pk_bf16_f32 v23, v24, v25
	v_cvt_pk_bf16_f32 v24, v28, v29
	v_cvt_pk_bf16_f32 v25, v26, v27
	global_store_dwordx4 v[68:69], v[22:25], off offset:256
	s_and_saveexec_b64 s[14:15], s[40:41]
	s_cbranch_execz .LBB0_149
	s_waitcnt lgkmcnt(0)
	v_add_f32_e32 v20, v20, v21
	v_add_f32_e32 v21, v18, v19
	v_lshl_add_u64 v[18:19], v[82:83], 3, s[56:57]
	global_atomic_add_f32 v[18:19], v21, off
	global_atomic_add_f32 v[18:19], v20, off offset:4
; DI u32x4 pack8(f32x4 a, f32x4 b) { u32x4 w; w.x = pk2(a[0], a[1]); w.y = pk2(a[2], a[3]); w.z = pk2(b[0], b[1]); w.w = pk2(b[2], b[3]); return w; }
;     DI void operator()(AccRef acc, const Unit& u, int wr, int wc, int fr, int fq) const {
;     ...
;             int row_ = row0 + ai * 128 + m * 16; asm volatile("" : "+v"(row_)); const size_t off = (size_t)row_ * DM + c0; float s1 = 0.f, s2 = 0.f;
; #pragma unroll
;             for (int bj = 0; bj < 2; ++bj) { f32x4 y[2];
; #pragma unroll
;                 for (int n = 0; n < 2; ++n) { y[n] = xb[cur][bj][n] * ALPHA + acc[ai][bj][m][n]; *(f32x4*)(Y + off + bj * 128 + 4 * n) = y[n];
;                     s1 += (y[n][0] + y[n][1]) + (y[n][2] + y[n][3]); s2 += (y[n][0] * y[n][0] + y[n][1] * y[n][1]) + (y[n][2] * y[n][2] + y[n][3] * y[n][3]); }
;                 const f32x4 g0 = *(const f32x4*)(G + c0 + bj * 128), g1 = *(const f32x4*)(G + c0 + bj * 128 + 4);
;                 *(u32x4*)(YG + off + bj * 128) = pack8(y[0] * g0, y[1] * g1); }
;             s1 += __shfl_xor(s1, 16); s1 += __shfl_xor(s1, 32); s2 += __shfl_xor(s2, 16); s2 += __shfl_xor(s2, 32);
;             if (fq == 0) { unsafeAtomicAdd(ST + (size_t)row_ * 2, s1); unsafeAtomicAdd(ST + (size_t)row_ * 2 + 1, s2); } }
.LBB0_149:
	s_or_b64 exec, exec, s[14:15]
	v_pk_fma_f32 v[16:17], v[48:49], s[30:31], v[16:17] op_sel_hi:[1,0,1]
	v_ashrrev_i32_e32 v67, 31, v66
	s_waitcnt lgkmcnt(0)
	v_lshlrev_b64 v[18:19], 10, v[66:67]
	v_lshl_add_u64 v[30:31], v[18:19], 0, v[168:169]
	v_lshl_add_u64 v[32:33], v[30:31], 2, s[60:61]
	v_pk_fma_f32 v[14:15], v[46:47], s[30:31], v[14:15] op_sel_hi:[1,0,1]
	v_pk_fma_f32 v[12:13], v[44:45], s[30:31], v[12:13] op_sel_hi:[1,0,1]
	v_pk_fma_f32 v[10:11], v[42:43], s[30:31], v[10:11] op_sel_hi:[1,0,1]
	global_store_dwordx4 v[32:33], v[14:17], off
	global_store_dwordx4 v[32:33], v[10:13], off offset:16
	global_load_dwordx4 v[18:21], v[170:171], off
	global_load_dwordx4 v[22:25], v[170:171], off offset:16
	v_pk_fma_f32 v[28:29], v[36:37], s[30:31], v[4:5] op_sel_hi:[1,0,1]
	v_pk_fma_f32 v[26:27], v[34:35], s[30:31], v[2:3] op_sel_hi:[1,0,1]
	v_lshl_add_u64 v[30:31], v[30:31], 1, s[58:59]
	v_pk_fma_f32 v[8:9], v[40:41], s[30:31], v[8:9] op_sel_hi:[1,0,1]
	v_pk_fma_f32 v[6:7], v[38:39], s[30:31], v[6:7] op_sel_hi:[1,0,1]
	v_mul_f32_e32 v35, v8, v8
	v_mul_f32_e32 v34, v7, v7
	v_mul_f32_e32 v38, v27, v27
	v_mul_f32_e32 v39, v28, v28
	v_fmac_f32_e32 v34, v6, v6
	v_fmac_f32_e32 v35, v9, v9
	v_add_f32_e32 v36, v26, v27
	v_add_f32_e32 v37, v29, v28
	v_fmac_f32_e32 v38, v26, v26
	v_fmac_f32_e32 v39, v29, v29
	s_waitcnt vmcnt(0)
	v_pk_mul_f32 v[4:5], v[16:17], v[20:21]
	v_pk_mul_f32 v[2:3], v[14:15], v[18:19]
	v_pk_mul_f32 v[18:19], v[12:13], v[24:25]
	v_pk_mul_f32 v[20:21], v[10:11], v[22:23]
	v_cvt_pk_bf16_f32 v2, v2, v3
	v_cvt_pk_bf16_f32 v3, v4, v5
	v_cvt_pk_bf16_f32 v4, v20, v21
	v_cvt_pk_bf16_f32 v5, v18, v19
	global_store_dwordx4 v[30:31], v[2:5], off
	global_store_dwordx4 v[32:33], v[6:9], off offset:512
	global_store_dwordx4 v[32:33], v[26:29], off offset:528
	global_load_dwordx4 v[18:21], v[170:171], off offset:512
	global_load_dwordx4 v[22:25], v[170:171], off offset:528
	v_add_f32_e32 v2, v14, v15
	v_add_f32_e32 v3, v17, v16
	v_mul_f32_e32 v4, v15, v15
	v_mul_f32_e32 v5, v16, v16
	v_add_f32_e32 v15, v10, v11
	v_add_f32_e32 v16, v13, v12
	v_mul_f32_e32 v11, v11, v11
	v_mul_f32_e32 v12, v12, v12
	v_add_f32_e32 v2, v2, v3
	v_fmac_f32_e32 v4, v14, v14
	v_fmac_f32_e32 v5, v17, v17
	v_fmac_f32_e32 v11, v10, v10
	v_fmac_f32_e32 v12, v13, v13
	v_add_f32_e32 v32, v6, v7
	v_add_f32_e32 v33, v9, v8
	v_add_f32_e32 v3, v15, v16
	v_add_f32_e32 v2, 0, v2
	v_add_f32_e32 v4, v4, v5
	v_add_f32_e32 v5, v11, v12
	v_add_f32_e32 v10, v32, v33
	v_add_f32_e32 v11, v34, v35
	v_add_f32_e32 v2, v2, v3
	v_add_f32_e32 v3, v4, v5
	v_add_f32_e32 v13, v36, v37
	v_add_f32_e32 v12, v38, v39
	v_add_f32_e32 v2, v2, v10
	v_add_f32_e32 v3, v3, v11
	v_add_f32_e32 v2, v2, v13
	v_add_f32_e32 v3, v3, v12
	v_mov_b32_e32 v4, v2
	v_mov_b32_e32 v240, v2
	s_nop 1
	v_permlane16_swap_b32_e32 v4, v240
	s_nop 1
	v_mov_b32_dpp v4, v240 quad_perm:[0,1,2,3] row_mask:0x5 bank_mask:0xf
	v_mov_b32_e32 v5, v3
	v_mov_b32_e32 v240, v3
	s_nop 1
	v_permlane16_swap_b32_e32 v5, v240
	s_nop 1
	v_mov_b32_dpp v5, v240 quad_perm:[0,1,2,3] row_mask:0x5 bank_mask:0xf
	s_waitcnt lgkmcnt(0)
	v_add_f32_e32 v2, v2, v4
	v_add_f32_e32 v4, v3, v5
	v_mov_b32_e32 v3, v2
	v_mov_b32_e32 v240, v2
	s_nop 1
	v_permlane32_swap_b32_e32 v3, v240
	s_nop 1
	v_mov_b32_dpp v3, v240 quad_perm:[0,1,2,3] row_mask:0x3 bank_mask:0xf
	v_mov_b32_e32 v5, v4
	v_mov_b32_e32 v240, v4
	s_nop 1
	v_permlane32_swap_b32_e32 v5, v240
	s_nop 1
	v_mov_b32_dpp v5, v240 quad_perm:[0,1,2,3] row_mask:0x3 bank_mask:0xf
	s_waitcnt vmcnt(0)
	v_pk_mul_f32 v[8:9], v[8:9], v[20:21]
	v_pk_mul_f32 v[6:7], v[6:7], v[18:19]
	v_pk_mul_f32 v[10:11], v[28:29], v[24:25]
	v_pk_mul_f32 v[12:13], v[26:27], v[22:23]
	v_cvt_pk_bf16_f32 v6, v6, v7
	v_cvt_pk_bf16_f32 v7, v8, v9
	v_cvt_pk_bf16_f32 v8, v12, v13
	v_cvt_pk_bf16_f32 v9, v10, v11
	global_store_dwordx4 v[30:31], v[6:9], off offset:256
	s_and_saveexec_b64 s[14:15], s[40:41]
	s_cbranch_execz .LBB0_151
	s_waitcnt lgkmcnt(0)
	v_add_f32_e32 v4, v4, v5
	v_add_f32_e32 v5, v2, v3
	v_lshl_add_u64 v[2:3], v[66:67], 3, s[56:57]
	global_atomic_add_f32 v[2:3], v5, off
	global_atomic_add_f32 v[2:3], v4, off offset:4
